# same as previous best but 256 (not 384) weight-queue grabs moved to the out-proj start
# speedup vs baseline: 1.0054x; 1.0054x over previous
.Lwq_entry:
	s_movk_i32 s99, 0
	s_cmp_lg_u32 s98, 0
	s_cmovk_i32 s99, 0xf000
	s_movk_i32 s0, 0x4200
	v_mad_u32_u24 v0, v195, s0, 0
	v_lshrrev_b32_e32 v34, 5, v192
	v_lshl_add_u32 v3, v196, 2, v0
	s_movk_i32 s0, 0x84
	v_mad_u32_u24 v35, v34, s0, v3
	s_add_u32 s0, s78, 0x600000
	s_addc_u32 s1, s79, 0
	s_add_u32 s2, s78, 0x800000
	s_addc_u32 s3, s79, 0
	v_lshlrev_b32_e32 v4, 3, v193
	s_add_u32 s4, s78, 0x4800000
	v_lshrrev_b32_e32 v2, 3, v192
	v_and_b32_e32 v4, 56, v4
	s_addc_u32 s5, s79, 0
	v_mul_u32_u24_e32 v6, 0x84, v4
	v_lshlrev_b32_e32 v7, 2, v2
	v_lshlrev_b32_e32 v2, 10, v2
	s_add_u32 s6, s78, 0x200000
	v_lshl_add_u32 v32, v195, 1, s99
	v_mul_u32_u24_e32 v5, 0x84, v34
	v_add3_u32 v36, v0, v6, v7
	v_or_b32_e32 v6, 0x2000, v2
	v_or_b32_e32 v8, 0x4000, v2
	v_or_b32_e32 v10, 0x6000, v2
	s_addc_u32 s7, s79, 0
	s_add_i32 s11, 0, 0x222e0
	v_add_u32_e32 v33, 0x580, v32
	v_mov_b32_e32 v1, 0
	s_movk_i32 s10, 0x2000
	v_mov_b32_e32 v37, s11
	s_movk_i32 s24, 0x34f
	s_cmp_lg_u32 s98, 0
	s_cmovk_i32 s24, 0x54f
	s_movk_i32 s25, 0x37f
	s_movk_i32 s30, 0x57f
	s_movk_i32 s31, 0x1fff
	s_mov_b64 s[8:9], 0x40000
	s_mov_b32 s33, 0x92492493
	v_lshlrev_b32_e32 v0, 2, v196
	v_add_u32_e32 v38, v3, v5
	v_lshlrev_b32_e32 v2, 1, v2
	v_lshlrev_b32_e32 v4, 1, v4
	v_lshlrev_b32_e32 v6, 1, v6
	v_lshlrev_b32_e32 v8, 1, v8
	v_lshlrev_b32_e32 v10, 1, v10
	s_branch .LBB0_461
